# FFT input read from a quad-major scratch written by the in-projection epilogue (coalesced); attention output transposed through LDS for full-line 16-byte stores
# speedup vs baseline: 1.0207x; 1.0083x over previous
; __device__ __forceinline__ unsigned pk2(float lo, float hi) { unsigned r; asm volatile("v_cvt_pk_bf16_f32 %0, %1, %2" : "=v"(r) : "v"(lo), "v"(hi)); return r; }
; __device__ void attn_item(const Params& p, int l, int item, LAS unsigned char* lds) {
;     ...
;     const float sink = p.attn_sink[l * 8 + head] * LOG2E;
;     const float inv = 1.f / (lrun + __builtin_amdgcn_exp2f(sink - mrun));
;     bf16_t* orow = AM + (size_t)(qrow0 + qq) * 1280 + head * 64;
; #pragma unroll
;     for (int dt = 0; dt < 2; ++dt)
; #pragma unroll
;         for (int rq = 0; rq < 4; ++rq) {
;             u32x2 o; o.x = pk2(ot[dt][4 * rq] * inv, ot[dt][4 * rq + 1] * inv); o.y = pk2(ot[dt][4 * rq + 2] * inv, ot[dt][4 * rq + 3] * inv);
;             *(u32x2*)(orow + 32 * dt + 8 * rq + 4 * hi) = o;
;         }
.LBB0_35:
	s_add_i32 s4, s15, s28
	s_ashr_i32 s5, s4, 31
	s_lshl_b64 s[4:5], s[4:5], 2
	v_lshl_add_u64 v[34:35], v[130:131], 0, s[4:5]
	global_load_dword v32, v[34:35], off
	v_readfirstlane_b32 s22, v140
	v_readfirstlane_b32 s23, v141
	v_readfirstlane_b32 s6, v138
	v_readfirstlane_b32 s7, v139
	s_nop 3
	s_add_u32 s22, s22, s6
	s_addc_u32 s23, s23, s7
	s_lshl_b64 s[6:7], s[20:21], 1
	s_add_u32 s22, s22, s6
	s_addc_u32 s23, s23, s7
	v_and_b32_e32 v40, 63, v210
	v_readfirstlane_b32 s6, v210
	v_and_b32_e32 v41, 31, v40
	v_lshrrev_b32_e32 v42, 5, v40
	s_lshr_b32 s6, s6, 6
	s_mul_i32 s6, s6, 0x1200
	s_add_i32 s6, s6, 0x18000
	v_mul_u32_u24_e32 v41, 0x90, v41
	v_lshl_add_u32 v41, v42, 3, v41
	v_add_u32_e32 v41, s6, v41
	v_lshrrev_b32_e32 v42, 3, v40
	v_and_b32_e32 v40, 7, v40
	v_lshlrev_b32_e32 v40, 4, v40
	v_mul_u32_u24_e32 v43, 0x90, v42
	v_add3_u32 v43, v43, v40, s6
	v_mul_u32_u24_e32 v42, 0xa00, v42
	v_add_u32_e32 v42, v42, v40
	s_movk_i32 s31, 0x1ff
	s_movk_i32 s34, 0xfc7f
	s_waitcnt vmcnt(0) lgkmcnt(0)
	v_fma_f32 v32, v32, s30, -v225
	v_exp_f32_e32 v32, v32
	s_nop 0
	v_add_f32_e32 v36, v33, v32
	v_div_scale_f32 v37, s[4:5], v36, v36, 1.0
	v_rcp_f32_e32 v38, v37
	s_nop 0
	v_div_scale_f32 v34, vcc, 1.0, v36, 1.0
	v_fma_f32 v35, -v37, v38, 1.0
	v_fmac_f32_e32 v38, v35, v38
	v_mul_f32_e32 v35, v34, v38
	v_fma_f32 v39, -v37, v35, v34
	v_fmac_f32_e32 v35, v39, v38
	v_fma_f32 v34, -v37, v35, v34
	v_div_fmas_f32 v34, v34, v38, v35
	v_div_fixup_f32 v34, v34, v36, 1.0
	v_mul_f32_e32 v16, v16, v34
	v_mul_f32_e32 v17, v17, v34
	v_mul_f32_e32 v18, v18, v34
	v_mul_f32_e32 v19, v19, v34
	v_mul_f32_e32 v20, v20, v34
	v_mul_f32_e32 v21, v21, v34
	v_mul_f32_e32 v22, v22, v34
	v_mul_f32_e32 v23, v23, v34
	v_mul_f32_e32 v24, v24, v34
	v_mul_f32_e32 v25, v25, v34
	v_mul_f32_e32 v26, v26, v34
	v_mul_f32_e32 v27, v27, v34
	v_mul_f32_e32 v28, v28, v34
	v_mul_f32_e32 v29, v29, v34
	v_mul_f32_e32 v30, v30, v34
	v_mul_f32_e32 v31, v31, v34
	v_mul_f32_e32 v0, v0, v34
	v_mul_f32_e32 v1, v1, v34
	v_mul_f32_e32 v2, v2, v34
	v_mul_f32_e32 v3, v3, v34
	v_mul_f32_e32 v4, v4, v34
	v_mul_f32_e32 v5, v5, v34
	v_mul_f32_e32 v6, v6, v34
	v_mul_f32_e32 v7, v7, v34
	v_mul_f32_e32 v8, v8, v34
	v_mul_f32_e32 v9, v9, v34
	v_mul_f32_e32 v10, v10, v34
	v_mul_f32_e32 v11, v11, v34
	v_mul_f32_e32 v12, v12, v34
	v_mul_f32_e32 v13, v13, v34
	v_mul_f32_e32 v14, v14, v34
	v_mul_f32_e32 v15, v15, v34
	v_cvt_pk_bf16_f32 v48, v16, v17
	v_cvt_pk_bf16_f32 v49, v18, v19
	v_cvt_pk_bf16_f32 v50, v20, v21
	v_cvt_pk_bf16_f32 v51, v22, v23
	v_cvt_pk_bf16_f32 v52, v24, v25
	v_cvt_pk_bf16_f32 v53, v26, v27
	v_cvt_pk_bf16_f32 v54, v28, v29
	v_cvt_pk_bf16_f32 v55, v30, v31
	v_cvt_pk_bf16_f32 v56, v0, v1
	v_cvt_pk_bf16_f32 v57, v2, v3
	v_cvt_pk_bf16_f32 v58, v4, v5
	v_cvt_pk_bf16_f32 v59, v6, v7
	v_cvt_pk_bf16_f32 v60, v8, v9
	v_cvt_pk_bf16_f32 v61, v10, v11
	v_cvt_pk_bf16_f32 v62, v12, v13
	v_cvt_pk_bf16_f32 v63, v14, v15
	ds_write_b64 v41, v[48:49]
	ds_write_b64 v41, v[50:51] offset:16
	ds_write_b64 v41, v[52:53] offset:32
	ds_write_b64 v41, v[54:55] offset:48
	ds_write_b64 v41, v[56:57] offset:64
	ds_write_b64 v41, v[58:59] offset:80
	ds_write_b64 v41, v[60:61] offset:96
	ds_write_b64 v41, v[62:63] offset:112
	s_waitcnt lgkmcnt(0)
	ds_read_b128 v[48:51], v43
	ds_read_b128 v[52:55], v43 offset:1152
	ds_read_b128 v[56:59], v43 offset:2304
	ds_read_b128 v[60:63], v43 offset:3456
	s_waitcnt lgkmcnt(3)
	global_store_dwordx4 v42, v[48:51], s[22:23]
	s_add_u32 s22, s22, 0x5000
	s_addc_u32 s23, s23, 0
	s_waitcnt lgkmcnt(2)
	global_store_dwordx4 v42, v[52:55], s[22:23]
	s_add_u32 s22, s22, 0x5000
	s_addc_u32 s23, s23, 0
	s_waitcnt lgkmcnt(1)
	global_store_dwordx4 v42, v[56:59], s[22:23]
	s_add_u32 s22, s22, 0x5000
	s_addc_u32 s23, s23, 0
	s_waitcnt lgkmcnt(0)
	global_store_dwordx4 v42, v[60:63], s[22:23]

; #define GAS __attribute__((address_space(1)))
; __device__ void fft_item(const Params& p, int item, bool isctx, LAS unsigned char* lds) {
;     ...
;     __syncthreads();
;     {
;         GAS const bf16_t* src = (GAS const bf16_t*)(unsigned long long)(p.ws + OFF_P1) + (size_t)rowbase * P1LD + 1024 + quad * 4;
;         u32x2 v[8];
; #pragma unroll
;         for (int q = 0; q < 8; ++q) { const int t = tid + 512 * q; v[q] = (t < N) ? *(GAS const u32x2*)(src + (size_t)t * P1LD) : (u32x2){0u, 0u}; }
;         asm volatile("" ::: "memory");
.LBB0_40:
	s_andn2_b64 vcc, exec, s[4:5]
	s_cbranch_vccnz .LBB0_176
	s_sub_i32 s6, s29, s10
	s_and_b32 s15, s6, 63
	s_cmpk_gt_i32 s6, 0xff
	s_mov_b64 s[4:5], -1
	s_cbranch_scc0 .LBB0_103
	s_lshl_b32 s22, s6, 2
	s_add_i32 s2, s22, 0x7ffffc00
	s_and_b32 s7, s2, 0x7fffff00
	s_addk_i32 s7, 0x4000
	s_mul_hi_u32 s5, s7, 0xa00
	s_mul_i32 s4, s7, 0xa00
	v_mov_b32_e32 v18, v210
	s_sub_u32 s4, s7, 0x4000
	s_lshl_b32 s4, s4, 9
	s_lshl_b32 s5, s15, 11
	s_add_u32 s4, s4, s5
	s_add_u32 s4, s4, 0xce00000
	s_mov_b32 s5, 0
	s_lshl_b32 s2, s15, 3
	v_lshl_add_u64 v[14:15], v[132:133], 0, s[4:5]
	s_movk_i32 s4, 0x100
	v_cmp_gt_i32_e32 vcc, s4, v18
	v_mov_b32_e32 v0, 0
	v_mov_b32_e32 v6, 0
	v_mov_b32_e32 v7, 0
	s_waitcnt lgkmcnt(0)
	s_barrier
	s_and_saveexec_b64 s[4:5], vcc
	s_cbranch_execz .LBB0_44
	v_mad_i64_i32 v[2:3], s[18:19], v18, 8, v[14:15]
	global_load_dwordx2 v[6:7], v[2:3], off
.LBB0_44:
	s_or_b64 exec, exec, s[4:5]
	v_add_u32_e32 v19, 0x200, v18
	v_cmp_gt_i32_e64 s[40:41], s63, v18
	v_mov_b32_e32 v1, 0
	s_and_saveexec_b64 s[4:5], s[40:41]
	s_cbranch_execz .LBB0_46
	v_mad_i64_i32 v[0:1], s[18:19], v19, 8, v[14:15]
	global_load_dwordx2 v[0:1], v[0:1], off
.LBB0_46:
	s_or_b64 exec, exec, s[4:5]
	s_movk_i32 s4, 0xfd00
	v_cmp_gt_i32_e64 s[42:43], s4, v18
	v_mov_b32_e32 v2, 0
	v_mov_b32_e32 v10, 0
	v_mov_b32_e32 v11, 0
	s_and_saveexec_b64 s[4:5], s[42:43]
	s_cbranch_execz .LBB0_48
	v_add_u32_e32 v3, 0x400, v18
	v_mad_i64_i32 v[4:5], s[18:19], v3, 8, v[14:15]
	global_load_dwordx2 v[10:11], v[4:5], off
.LBB0_48:
	s_or_b64 exec, exec, s[4:5]
	s_movk_i32 s4, 0xfb00
	v_cmp_gt_i32_e64 s[44:45], s4, v18
	v_mov_b32_e32 v3, 0
	s_and_saveexec_b64 s[4:5], s[44:45]
	s_cbranch_execz .LBB0_50
	v_add_u32_e32 v2, 0x600, v18
	v_mad_i64_i32 v[2:3], s[18:19], v2, 8, v[14:15]
	global_load_dwordx2 v[2:3], v[2:3], off
.LBB0_50:
	s_or_b64 exec, exec, s[4:5]
	s_movk_i32 s4, 0xf900
	v_cmp_gt_i32_e64 s[46:47], s4, v18
	v_mov_b32_e32 v4, 0
	v_mov_b32_e32 v12, 0
	v_mov_b32_e32 v13, 0
	s_and_saveexec_b64 s[4:5], s[46:47]
	s_cbranch_execz .LBB0_52
	v_add_u32_e32 v5, 0x800, v18
	v_mad_i64_i32 v[8:9], s[18:19], v5, 8, v[14:15]
	global_load_dwordx2 v[12:13], v[8:9], off
.LBB0_52:
	s_or_b64 exec, exec, s[4:5]
	s_movk_i32 s4, 0xf700
	v_cmp_gt_i32_e64 s[48:49], s4, v18
	v_mov_b32_e32 v5, 0
	s_and_saveexec_b64 s[4:5], s[48:49]
	s_cbranch_execz .LBB0_54
	v_add_u32_e32 v4, 0xa00, v18
	v_mad_i64_i32 v[4:5], s[18:19], v4, 8, v[14:15]
	global_load_dwordx2 v[4:5], v[4:5], off
.LBB0_54:
	s_or_b64 exec, exec, s[4:5]
	s_movk_i32 s4, 0xf500
	v_cmp_gt_i32_e64 s[50:51], s4, v18
	v_mov_b32_e32 v8, 0
	v_mov_b32_e32 v16, 0
	v_mov_b32_e32 v17, 0
	s_and_saveexec_b64 s[4:5], s[50:51]
	s_cbranch_execz .LBB0_56
	v_add_u32_e32 v9, 0xc00, v18
	v_mad_i64_i32 v[16:17], s[18:19], v9, 8, v[14:15]
	global_load_dwordx2 v[16:17], v[16:17], off
.LBB0_56:
	s_or_b64 exec, exec, s[4:5]
	s_movk_i32 s4, 0xf300
	v_cmp_gt_i32_e64 s[52:53], s4, v18
	v_mov_b32_e32 v9, 0
	s_and_saveexec_b64 s[4:5], s[52:53]
	s_cbranch_execz .LBB0_58
	v_add_u32_e32 v8, 0xe00, v18
	v_mad_i64_i32 v[8:9], s[18:19], v8, 8, v[14:15]
	global_load_dwordx2 v[8:9], v[8:9], off

; #define GAS __attribute__((address_space(1)))
; __device__ void fft_item(const Params& p, int item, bool isctx, LAS unsigned char* lds) {
;     ...
;     __syncthreads();
;     {
;         GAS const bf16_t* src = (GAS const bf16_t*)(unsigned long long)(p.ws + OFF_P1) + (size_t)rowbase * P1LD + 1024 + quad * 4;
;         u32x2 v[8];
; #pragma unroll
;         for (int q = 0; q < 8; ++q) { const int t = tid + 512 * q; v[q] = (t < N) ? *(GAS const u32x2*)(src + (size_t)t * P1LD) : (u32x2){0u, 0u}; }
;         asm volatile("" ::: "memory");
.LBB0_103:
	s_and_b64 vcc, exec, s[4:5]
	s_cbranch_vccz .LBB0_176
	s_lshl_b32 s2, s6, 6
	s_and_b32 s7, s2, 0xfffff000
	s_mul_hi_i32 s5, s7, 0xa00
	s_mul_i32 s4, s7, 0xa00
	v_mov_b32_e32 v18, v210
	s_lshl_b32 s4, s7, 9
	s_lshl_b32 s5, s15, 15
	s_add_u32 s4, s4, s5
	s_add_u32 s4, s4, 0xc600000
	s_mov_b32 s5, 0
	s_lshl_b32 s2, s15, 3
	v_lshl_add_u64 v[14:15], v[132:133], 0, s[4:5]
	v_cmp_gt_i32_e32 vcc, s73, v18
	v_mov_b32_e32 v0, 0
	v_mov_b32_e32 v6, 0
	v_mov_b32_e32 v7, 0
	s_waitcnt lgkmcnt(0)
	s_barrier
	s_and_saveexec_b64 s[4:5], vcc
	s_cbranch_execz .LBB0_106
	v_mad_i64_i32 v[2:3], s[18:19], v18, 8, v[14:15]
	global_load_dwordx2 v[6:7], v[2:3], off
.LBB0_106:
	s_or_b64 exec, exec, s[4:5]
	s_movk_i32 s4, 0xe00
	v_add_u32_e32 v19, 0x200, v18
	v_cmp_gt_i32_e64 s[42:43], s4, v18
	v_mov_b32_e32 v1, 0
	s_and_saveexec_b64 s[4:5], s[42:43]
	s_cbranch_execz .LBB0_108
	v_mad_i64_i32 v[0:1], s[18:19], v19, 8, v[14:15]
	global_load_dwordx2 v[0:1], v[0:1], off
.LBB0_108:
	s_or_b64 exec, exec, s[4:5]
	s_movk_i32 s4, 0xc00
	v_cmp_gt_i32_e64 s[44:45], s4, v18
	v_mov_b32_e32 v2, 0
	v_mov_b32_e32 v10, 0
	v_mov_b32_e32 v11, 0
	s_and_saveexec_b64 s[4:5], s[44:45]
	s_movk_i32 s11, 0x3ff
	s_mov_b32 s15, 0x8d80000
	s_cbranch_execz .LBB0_110
	v_add_u32_e32 v3, 0x400, v18
	v_mad_i64_i32 v[4:5], s[18:19], v3, 8, v[14:15]
	global_load_dwordx2 v[10:11], v[4:5], off
.LBB0_110:
	s_or_b64 exec, exec, s[4:5]
	v_cmp_gt_i32_e64 s[46:47], s38, v18
	v_mov_b32_e32 v3, 0
	s_and_saveexec_b64 s[4:5], s[46:47]
	s_cbranch_execz .LBB0_112
	v_add_u32_e32 v2, 0x600, v18
	v_mad_i64_i32 v[2:3], s[18:19], v2, 8, v[14:15]
	global_load_dwordx2 v[2:3], v[2:3], off
.LBB0_112:
	s_or_b64 exec, exec, s[4:5]
	s_movk_i32 s4, 0x800
	v_cmp_gt_i32_e64 s[40:41], s4, v18
	v_mov_b32_e32 v4, 0
	v_mov_b32_e32 v12, 0
	v_mov_b32_e32 v13, 0
	s_and_saveexec_b64 s[4:5], s[40:41]
	s_cbranch_execz .LBB0_114
	v_add_u32_e32 v5, 0x800, v18
	v_mad_i64_i32 v[8:9], s[18:19], v5, 8, v[14:15]
	global_load_dwordx2 v[12:13], v[8:9], off
.LBB0_114:
	s_or_b64 exec, exec, s[4:5]
	s_movk_i32 s4, 0x600
	v_cmp_gt_i32_e64 s[48:49], s4, v18
	v_mov_b32_e32 v5, 0
	s_and_saveexec_b64 s[4:5], s[48:49]
	s_cbranch_execz .LBB0_116
	v_add_u32_e32 v4, 0xa00, v18
	v_mad_i64_i32 v[4:5], s[18:19], v4, 8, v[14:15]
	global_load_dwordx2 v[4:5], v[4:5], off
.LBB0_116:
	s_or_b64 exec, exec, s[4:5]
	s_movk_i32 s4, 0x400
	v_cmp_gt_i32_e64 s[50:51], s4, v18
	v_mov_b32_e32 v8, 0
	v_mov_b32_e32 v16, 0
	v_mov_b32_e32 v17, 0
	s_and_saveexec_b64 s[4:5], s[50:51]
	s_cbranch_execz .LBB0_118
	v_add_u32_e32 v9, 0xc00, v18
	v_mad_i64_i32 v[16:17], s[18:19], v9, 8, v[14:15]
	global_load_dwordx2 v[16:17], v[16:17], off
.LBB0_118:
	s_or_b64 exec, exec, s[4:5]
	s_movk_i32 s4, 0x200
	v_cmp_gt_i32_e64 s[52:53], s4, v18
	v_mov_b32_e32 v9, 0
	s_and_saveexec_b64 s[4:5], s[52:53]
	s_cbranch_execz .LBB0_120
	v_add_u32_e32 v8, 0xe00, v18
	v_mad_i64_i32 v[8:9], s[18:19], v8, 8, v[14:15]
	global_load_dwordx2 v[8:9], v[8:9], off

; __device__ __forceinline__ unsigned pk2(float lo, float hi) { unsigned r; asm volatile("v_cvt_pk_bf16_f32 %0, %1, %2" : "=v"(r) : "v"(lo), "v"(hi)); return r; }
; #define GAS __attribute__((address_space(1)))
; template <class T> __device__ __forceinline__ GAS T* gptr(T* q) { return (GAS T*)(unsigned long long)uptr(q); }
; __device__ __forceinline__ void gemm_epilogue(LAS unsigned char* lds, const GD& gd, const f32x4 (&acc)[2][2][4][2], const Unit& u) {
;     ...
;     int ldc = __builtin_amdgcn_readfirstlane(gd.ldc);
;     const int lcol = wc * 32 + 8 * fq;
;     const bool ctx_gate_out = (mode == M_P1) && (u.pn >= 5);
;     const bool ctx_gate_in = (row_u >= NL) && (gd.auxc != nullptr);
;     const int emode = ctx_gate_out ? (int)M_GATE : mode;
;     if (ctx_gate_out) ldc = 3072;
;     const int apitch = ctx_gate_in ? 3072 : 1024;
;     GAS bf16_t* outu = gptr(ctx_gate_out ? gd.auxc + (size_t)(row_u - NL) * 3072 + (u.pn - 5) * BM : gd.out + (size_t)row_u * ldc + u.pn * BM);
;     GAS const bf16_t* auxu = gptr(ctx_gate_in ? (const bf16_t*)gd.auxc + (size_t)(row_u - NL) * 3072 + u.pn * BM : gd.aux + (size_t)row_u * 1024 + u.pn * BM);
;     const unsigned ooff = (unsigned)(lrow * ldc + lcol), goff = (unsigned)(lrow * apitch + lcol);
;     ...
;             u32x4 w; w.x = pk2(v0[0], v0[1]); w.y = pk2(v0[2], v0[3]); w.z = pk2(v1[0], v1[1]); w.w = pk2(v1[2], v1[3]);
;             *(GAS u32x4*)(outu + ooff + (ai * HALF + m * 16) * ldc + bj * HALF) = w;
.LBB0_385:
	v_mov_b32_e32 v211, v210
	s_mov_b32 s78, s11
	s_xor_b64 s[86:87], s[4:5], -1
	v_readfirstlane_b32 s11, v211
	s_ashr_i32 s98, s11, 8
	s_bfe_u32 s15, s11, 0x20006
	s_lshl_b32 s88, s33, 8
	s_lshl_b32 s89, s98, 6
	v_and_b32_e32 v252, 15, v211
	v_bfe_u32 v251, v211, 4, 2
	s_cmp_lg_u32 s78, 0
	s_cbranch_scc1 .Lmy_noft
	s_cmp_lg_u32 s80, 4
	s_cbranch_scc1 .Lmy_noft
	v_mov_b32_e32 v132, 0x240a8
	ds_read_b64 v[132:133], v132
	s_waitcnt lgkmcnt(0)
	v_readfirstlane_b32 s46, v132
	v_readfirstlane_b32 s47, v133
	s_cmp_lt_i32 s33, 64
	s_cbranch_scc0 .Lmy_ft_ctx
	s_lshr_b32 s48, s33, 4
	s_lshl_b32 s48, s48, 21
	s_and_b32 s49, s33, 15
	s_lshl_b32 s49, s49, 11
	s_add_u32 s48, s48, s49
	s_add_u32 s48, s48, 0xc600000
	s_add_u32 s46, s46, s48
	s_addc_u32 s47, s47, 0
	s_mov_b32 s48, 15
	s_branch .Lmy_ft_go
.Lmy_ft_ctx:
	s_sub_u32 s48, s33, 64
	s_lshl_b32 s48, s48, 17
	s_add_u32 s48, s48, 0xce00000
	s_add_u32 s46, s46, s48
	s_addc_u32 s47, s47, 0
	s_mov_b32 s48, 11
.Lmy_ft_go:
	v_lshlrev_b32_e32 v152, 1, v251
	s_lshl_b32 s49, s15, 3
	v_add_u32_e32 v152, s49, v152
	v_or_b32_e32 v153, s89, v252
	v_lshlrev_b32_e32 v153, 3, v153
	v_lshl_add_u32 v148, v152, s48, v153
	v_add_u32_e32 v154, 1, v152
	v_lshl_add_u32 v149, v154, s48, v153
	v_add_u32_e32 v154, 32, v152
	v_lshl_add_u32 v150, v154, s48, v153
	v_add_u32_e32 v154, 33, v152
	v_lshl_add_u32 v151, v154, s48, v153
	v_cvt_pk_bf16_f32 v132, v126, v127
	v_cvt_pk_bf16_f32 v133, v128, v129
	global_store_dwordx2 v148, v[132:133], s[46:47]
	v_cvt_pk_bf16_f32 v134, v4, v5
	v_cvt_pk_bf16_f32 v135, v6, v7
	global_store_dwordx2 v149, v[134:135], s[46:47]
	v_cvt_pk_bf16_f32 v136, v48, v49
	v_cvt_pk_bf16_f32 v137, v50, v51
	global_store_dwordx2 v150, v[136:137], s[46:47]
	v_cvt_pk_bf16_f32 v138, v12, v13
	v_cvt_pk_bf16_f32 v139, v14, v15
	global_store_dwordx2 v151, v[138:139], s[46:47]
	v_cvt_pk_bf16_f32 v140, v122, v123
	v_cvt_pk_bf16_f32 v141, v124, v125
	global_store_dwordx2 v148, v[140:141], s[46:47] offset:128
	v_cvt_pk_bf16_f32 v142, v118, v119
	v_cvt_pk_bf16_f32 v143, v120, v121
	global_store_dwordx2 v149, v[142:143], s[46:47] offset:128
	v_cvt_pk_bf16_f32 v144, v102, v103
	v_cvt_pk_bf16_f32 v145, v104, v105
	global_store_dwordx2 v150, v[144:145], s[46:47] offset:128
	v_cvt_pk_bf16_f32 v146, v98, v99
	v_cvt_pk_bf16_f32 v147, v100, v101
	global_store_dwordx2 v151, v[146:147], s[46:47] offset:128
	v_cvt_pk_bf16_f32 v132, v114, v115
	v_cvt_pk_bf16_f32 v133, v116, v117
	global_store_dwordx2 v148, v[132:133], s[46:47] offset:256
	v_cvt_pk_bf16_f32 v134, v110, v111
	v_cvt_pk_bf16_f32 v135, v112, v113
	global_store_dwordx2 v149, v[134:135], s[46:47] offset:256
	v_cvt_pk_bf16_f32 v136, v92, v93
	v_cvt_pk_bf16_f32 v137, v94, v95
	global_store_dwordx2 v150, v[136:137], s[46:47] offset:256
	v_cvt_pk_bf16_f32 v138, v88, v89
	v_cvt_pk_bf16_f32 v139, v90, v91
	global_store_dwordx2 v151, v[138:139], s[46:47] offset:256
	v_cvt_pk_bf16_f32 v140, v106, v107
	v_cvt_pk_bf16_f32 v141, v108, v109
	global_store_dwordx2 v148, v[140:141], s[46:47] offset:384
	v_cvt_pk_bf16_f32 v142, v8, v9
	v_cvt_pk_bf16_f32 v143, v10, v11
	global_store_dwordx2 v149, v[142:143], s[46:47] offset:384
	v_cvt_pk_bf16_f32 v144, v44, v45
	v_cvt_pk_bf16_f32 v145, v46, v47
	global_store_dwordx2 v150, v[144:145], s[46:47] offset:384
	v_cvt_pk_bf16_f32 v146, v16, v17
	v_cvt_pk_bf16_f32 v147, v18, v19
	global_store_dwordx2 v151, v[146:147], s[46:47] offset:384
	v_cvt_pk_bf16_f32 v132, v84, v85
	v_cvt_pk_bf16_f32 v133, v86, v87
	global_store_dwordx2 v148, v[132:133], s[46:47] offset:1024
	v_cvt_pk_bf16_f32 v134, v20, v21
	v_cvt_pk_bf16_f32 v135, v22, v23
	global_store_dwordx2 v149, v[134:135], s[46:47] offset:1024
	v_cvt_pk_bf16_f32 v136, v40, v41
	v_cvt_pk_bf16_f32 v137, v42, v43
	global_store_dwordx2 v150, v[136:137], s[46:47] offset:1024
	v_cvt_pk_bf16_f32 v138, v28, v29
	v_cvt_pk_bf16_f32 v139, v30, v31
	global_store_dwordx2 v151, v[138:139], s[46:47] offset:1024
	v_cvt_pk_bf16_f32 v140, v80, v81
	v_cvt_pk_bf16_f32 v141, v82, v83
	global_store_dwordx2 v148, v[140:141], s[46:47] offset:1152
	v_cvt_pk_bf16_f32 v142, v76, v77
	v_cvt_pk_bf16_f32 v143, v78, v79
	global_store_dwordx2 v149, v[142:143], s[46:47] offset:1152
	v_cvt_pk_bf16_f32 v144, v60, v61
	v_cvt_pk_bf16_f32 v145, v62, v63
	global_store_dwordx2 v150, v[144:145], s[46:47] offset:1152
	v_cvt_pk_bf16_f32 v146, v56, v57
	v_cvt_pk_bf16_f32 v147, v58, v59
	global_store_dwordx2 v151, v[146:147], s[46:47] offset:1152
	v_cvt_pk_bf16_f32 v132, v72, v73
	v_cvt_pk_bf16_f32 v133, v74, v75
	global_store_dwordx2 v148, v[132:133], s[46:47] offset:1280
	v_cvt_pk_bf16_f32 v134, v68, v69
	v_cvt_pk_bf16_f32 v135, v70, v71
	global_store_dwordx2 v149, v[134:135], s[46:47] offset:1280
	v_cvt_pk_bf16_f32 v136, v52, v53
	v_cvt_pk_bf16_f32 v137, v54, v55
	global_store_dwordx2 v150, v[136:137], s[46:47] offset:1280
	v_cvt_pk_bf16_f32 v138, v0, v1
	v_cvt_pk_bf16_f32 v139, v2, v3
	global_store_dwordx2 v151, v[138:139], s[46:47] offset:1280
	v_cvt_pk_bf16_f32 v140, v64, v65
	v_cvt_pk_bf16_f32 v141, v66, v67
	global_store_dwordx2 v148, v[140:141], s[46:47] offset:1408
	v_cvt_pk_bf16_f32 v142, v24, v25
	v_cvt_pk_bf16_f32 v143, v26, v27
	global_store_dwordx2 v149, v[142:143], s[46:47] offset:1408
	v_cvt_pk_bf16_f32 v144, v36, v37
	v_cvt_pk_bf16_f32 v145, v38, v39
	global_store_dwordx2 v150, v[144:145], s[46:47] offset:1408
	v_cvt_pk_bf16_f32 v146, v32, v33
	v_cvt_pk_bf16_f32 v147, v34, v35
	global_store_dwordx2 v151, v[146:147], s[46:47] offset:1408
	s_branch .LBB0_622
; #define GAS __attribute__((address_space(1)))
; template <class T> __device__ __forceinline__ GAS T* gptr(T* q) { return (GAS T*)(unsigned long long)uptr(q); }
; __device__ __forceinline__ void gemm_epilogue(LAS unsigned char* lds, const GD& gd, const f32x4 (&acc)[2][2][4][2], const Unit& u) {
;     ...
;     if (mode == M_UPC) {
;         const int chl = wc * 32 + 8 * fq;
;         GAS const float* cwu = gptr(gd.cw + u.pn * 128);
;         f32x4 cwv[2][3], cwg[2][3];
; #pragma unroll
;         for (int n = 0; n < 2; ++n)
; #pragma unroll
;             for (int tp = 0; tp < 3; ++tp) { cwv[n][tp] = *(GAS const f32x4*)(cwu + tp * 5632 + chl + 4 * n); cwg[n][tp] = *(GAS const f32x4*)(cwu + tp * 5632 + DFF + chl + 4 * n); }
.Lmy_noft:
	s_mov_b64 s[6:7], -1
	s_mov_b64 s[92:93], 0
	s_cmp_lt_i32 s78, 6
	s_mov_b64 s[4:5], 0
	s_cbranch_scc1 .LBB0_390
	s_cmp_eq_u32 s78, 6
	s_mov_b64 s[4:5], -1
	s_cbranch_scc0 .LBB0_463
	s_lshl_b32 s48, s80, 7
	s_ashr_i32 s49, s48, 31
	s_lshl_b32 s94, s15, 5
	v_lshlrev_b32_e32 v184, 3, v251
	s_lshl_b64 s[4:5], s[48:49], 2
	v_or_b32_e32 v206, s94, v184
	v_lshl_add_u64 v[132:133], v[228:229], 0, s[4:5]
	v_lshlrev_b32_e32 v96, 2, v206
	v_readfirstlane_b32 s5, v133
	v_readfirstlane_b32 s4, v132
	s_nop 4
	global_load_dwordx4 v[136:139], v96, s[4:5] offset:16
	global_load_dwordx4 v[160:163], v96, s[4:5]
	v_lshl_add_u64 v[148:149], s[4:5], 0, v[96:97]
	v_add_co_u32_e32 v134, vcc, s14, v148
	s_mov_b64 s[4:5], 0x2c00
	s_nop 0
	v_addc_co_u32_e32 v135, vcc, 0, v149, vcc
	v_lshl_add_u64 v[132:133], v[148:149], 0, s[4:5]
	s_mov_b64 s[4:5], 0x5800
	v_add_co_u32_e32 v142, vcc, 0x5000, v148
	v_lshl_add_u64 v[140:141], v[148:149], 0, s[4:5]
	s_nop 0
	v_addc_co_u32_e32 v143, vcc, 0, v149, vcc
	s_mov_b64 s[4:5], 0x8400
	global_load_dwordx4 v[156:159], v[134:135], off offset:3072
	s_nop 0
	global_load_dwordx4 v[132:135], v[132:133], off offset:16
	s_nop 0
	global_load_dwordx4 v[168:171], v[142:143], off offset:2048
	global_load_dwordx4 v[144:147], v[140:141], off offset:16
	v_lshl_add_u64 v[140:141], v[148:149], 0, s[4:5]
	s_mov_b32 s4, 0x8000
	v_add_co_u32_e32 v142, vcc, s4, v148
	s_mov_b64 s[4:5], 0xb000
	s_nop 0
	v_addc_co_u32_e32 v143, vcc, 0, v149, vcc
	v_add_co_u32_e32 v152, vcc, 0xb000, v148
	v_lshl_add_u64 v[150:151], v[148:149], 0, s[4:5]
	s_nop 0
	v_addc_co_u32_e32 v153, vcc, 0, v149, vcc
	s_mov_b64 s[4:5], 0xdc00
	global_load_dwordx4 v[164:167], v[142:143], off offset:1024
	s_nop 0
	global_load_dwordx4 v[140:143], v[140:141], off offset:16
	s_nop 0
	global_load_dwordx4 v[176:179], v[152:153], off
	s_nop 0
	global_load_dwordx4 v[152:155], v[150:151], off offset:16
	v_lshl_add_u64 v[150:151], v[148:149], 0, s[4:5]
	v_add_co_u32_e32 v148, vcc, 0xd000, v148
	v_readlane_b32 s4, v254, 39
	s_nop 0
	v_addc_co_u32_e32 v149, vcc, 0, v149, vcc
	global_load_dwordx4 v[172:175], v[148:149], off offset:3072
	s_nop 0
	global_load_dwordx4 v[148:151], v[150:151], off offset:16
	v_lshl_add_u32 v241, v251, 6, s4
	s_lshl_b32 s4, s98, 11
	s_lshl_b32 s5, s15, 9
	s_or_b32 s4, s5, s4
	v_add_u32_e32 v96, s4, v241
	v_cmp_lt_i32_e32 vcc, 14, v252
	s_mov_b64 s[6:7], 0
	s_and_saveexec_b64 s[4:5], vcc
	s_xor_b64 s[4:5], exec, s[4:5]
	s_cbranch_execz .LBB0_398
	s_mov_b64 s[6:7], exec
	ds_write_b128 v96, v[106:109] offset:256
	s_andn2_saveexec_b64 s[4:5], s[4:5]
	s_cbranch_execnz .LBB0_399
